# A/B of strategy 4: static s_setprio 1 for waves 0-3 instead of 4-7, flips deleted
# speedup vs baseline: 1.0057x; 1.0035x over previous
; #define PG8_STAGE(bufoff, gbase, voff) do { _Pragma("unroll") for (int _i = 0; _i < 2; ++_i) \
;         __builtin_amdgcn_global_load_lds((const unsigned*)((const char*)(gbase) + (voff)[_i]), (LAS unsigned*)(lds + (bufoff) + ldsw + _i * 8192), 16, 0, 0); } while (0)
; #define PG8_LDA(dst, b, h) do { _Pragma("unroll") for (int m = 0; m < 4; ++m) _Pragma("unroll") for (int k = 0; k < 2; ++k) dst[m][k] = *(const LAS bf16x8*)(lds + PG8_SA(b, h) + aoff + m * 2048 + k * 1024); } while (0)
; #define PG8_LDB(dst, b, h) do { _Pragma("unroll") for (int n = 0; n < 2; ++n) _Pragma("unroll") for (int k = 0; k < 2; ++k) dst[n][k] = *(const LAS bf16x8*)(lds + PG8_SB(b, h) + boff + n * 2048 + k * 1024); } while (0)
; #define PG8_SCHED __builtin_amdgcn_sched_barrier(0)
; __device__ __forceinline__ void gemm_phase(const int bid, const int nblk, LAS unsigned char* lds, const int garg, const int chunk, const Params& p) {
;     ...
;         const bool has_next = next(ui + 1, nxt);
;         const char* nA = has_next ? nxt.A : cA; const char* nB = has_next ? nxt.B : cB;
;         for (int t = 0; t < nt; t += 2) {
;             const bool last = (t == nt - 2);
;             const char* a1 = cA + (size_t)(t + 1) * kstep;
;             const char* a2 = last ? nA : cA + (size_t)(t + 2) * kstep; const char* b2 = last ? nB : cB + (size_t)(t + 2) * kstep;
;             const char* a3 = a2 + kstep; const char* b3 = b2 + kstep;
;             PG8_LDB(B0, 0, 0); PG8_SCHED; PG8_LDA(At, 0, 0); PG8_STAGE(PG8_SA(1, 1), a1 + hstepA, voffA);
.LBB0_439:
	v_readlane_b32 s10, v254, 62
	v_readlane_b32 s11, v254, 63
	s_andn2_b64 vcc, exec, s[10:11]
	s_cbranch_vccnz .LBB0_442
	s_add_u32 s2, s2, 0x80
	s_addc_u32 s3, s3, 0
	s_add_u32 s14, s8, 0x100
	s_addc_u32 s15, s9, 0
	s_mov_b32 s8, 0
	v_readfirstlane_b32 s98, v169
	s_nop 3
	s_cmp_ge_u32 s98, 0x100
	s_cbranch_scc1 .Lprio_skip
	s_setprio 1
